# grid barriers 2..10: last XCC leader releases all XCCs directly (no TOPGEN poll / per-XCC relay stage), per-XCC arrival and leader-only L2 writeback kept
# baseline (speedup 1.0000x reference)
; __device__ __forceinline__ unsigned xb_ld(unsigned* p)              { return __hip_atomic_load(p, __ATOMIC_RELAXED, __HIP_MEMORY_SCOPE_AGENT); }
; __device__ __forceinline__ unsigned xb_add(unsigned* p, unsigned v) { return __hip_atomic_fetch_add(p, v, __ATOMIC_RELAXED, __HIP_MEMORY_SCOPE_AGENT); }
; __device__ __forceinline__ void xcd_barrier_complete(unsigned* bar, unsigned x, unsigned& nloc, unsigned& nx) {
;     const unsigned G = gridDim.x * gridDim.y * gridDim.z;
;     unsigned sum, cnt, mine, sp = 0u;
;     for (;;) {
;         sum = 0u; cnt = 0u; mine = 0u;
; #pragma unroll
;         for (unsigned j = 0; j < 16; ++j) { const unsigned c = xb_ld(&bar[XB_XCNT(j)]); sum += c; cnt += (c > 0u) ? 1u : 0u; mine = (j == x) ? c : mine; }
;         if (sum == G) break;
;         __builtin_amdgcn_s_sleep(1);
;         if ((++sp & 255u) == 0u) { if (xb_ld(&bar[XB_TMO])) break; if (sp > XB_SPIN_CAP) { atomicAdd(&bar[XB_TMO], 1u); break; } }
;     }
;     nloc = mine > 0u ? mine : 1u; nx = cnt > 0u ? cnt : 1u;
; }
; __device__ __forceinline__ void xcd_barrier(const XcdBarrier& b) {
;     asm volatile("s_waitcnt vmcnt(0)" ::: "memory");
;     __syncthreads();
;     if (threadIdx.x == 0) {
;         unsigned* bar = b.bar;
;         __builtin_amdgcn_s_waitcnt(0);
;         unsigned nloc = b.st[0], nx = b.st[1];
;         if (nloc == 0u) { xcd_barrier_complete(bar, b.x, nloc, nx); b.st[0] = nloc; b.st[1] = nx; }
;         const unsigned old = xb_add(&bar[XB_XSUB(b.x)], 1u);
;         const unsigned gen = old / nloc;
;         if (old + 1u == (gen + 1u) * nloc) {
;             __builtin_amdgcn_fence(__ATOMIC_RELEASE, "agent");
;             asm volatile("s_waitcnt vmcnt(0)" ::: "memory");
;             const unsigned og = xb_add(&bar[XB_TOP], 1u);
;             const unsigned tg = og / nx;
;             if (og + 1u == (tg + 1u) * nx) xb_add(&bar[XB_TOPGEN], 1u);
;             else XB_SPIN(xb_ld(&bar[XB_TOPGEN]) == tg, bar);
;             __builtin_amdgcn_fence(__ATOMIC_ACQUIRE, "agent");
;             xb_add(&bar[XB_XGEN(b.x)], 1u);
;             asm volatile("s_waitcnt vmcnt(0)" ::: "memory");
;         } else {
;             XB_SPIN(xb_ld(&bar[XB_XGEN(b.x)]) == gen, bar);
;             __builtin_amdgcn_fence(__ATOMIC_ACQUIRE, "agent");
;             asm volatile("s_waitcnt vmcnt(0)" ::: "memory");
;         }
;     }
.LBB0_325:
	s_waitcnt vmcnt(0)
	s_waitcnt vmcnt(0) lgkmcnt(0)
	s_barrier
	s_mov_b64 s[12:13], exec
	v_readlane_b32 s10, v252, 11
	v_readlane_b32 s11, v252, 12
	s_and_b64 s[10:11], s[12:13], s[10:11]
	s_mov_b64 exec, s[10:11]
	s_cbranch_execz .LBB0_324
	v_readlane_b32 s98, v252, 4
	v_readlane_b32 s99, v252, 5
	s_load_dword vcc_lo, s[98:99], 0xf8
	v_readlane_b32 s100, v252, 2
	v_readlane_b32 s101, v252, 3
	v_mov_b32_e32 v15, 0x22fc0
	ds_read_b32 v0, v15
	s_waitcnt lgkmcnt(0)
	v_add_u32_e32 v0, 1, v0
	ds_write_b32 v15, v0
	s_nop 0
	v_readfirstlane_b32 s98, v0
	ds_read_b32 v0, v15 offset:4
	s_waitcnt lgkmcnt(0)
	v_readfirstlane_b32 s99, v0
	s_mov_b32 m0, 0x400
	s_cmp_lg_u32 s99, 0
	s_cbranch_scc1 .Lhb0_have
.Lhb0_cen:
	v_mov_b32_e32 v16, 0x400
	global_load_dword v15, v16, s[100:101] sc1
	global_load_dword v0, v16, s[100:101] offset:256 sc1
	global_load_dword v1, v16, s[100:101] offset:512 sc1
	global_load_dword v2, v16, s[100:101] offset:768 sc1
	global_load_dword v3, v16, s[100:101] offset:1024 sc1
	global_load_dword v4, v16, s[100:101] offset:1280 sc1
	global_load_dword v5, v16, s[100:101] offset:1536 sc1
	global_load_dword v6, v16, s[100:101] offset:1792 sc1
	global_load_dword v7, v16, s[100:101] offset:2048 sc1
	global_load_dword v8, v16, s[100:101] offset:2304 sc1
	global_load_dword v9, v16, s[100:101] offset:2560 sc1
	global_load_dword v10, v16, s[100:101] offset:2816 sc1
	global_load_dword v11, v16, s[100:101] offset:3072 sc1
	global_load_dword v12, v16, s[100:101] offset:3328 sc1
	global_load_dword v13, v16, s[100:101] offset:3584 sc1
	global_load_dword v14, v16, s[100:101] offset:3840 sc1
	v_readlane_b32 vcc_hi, v252, 10
	s_lshl_b32 vcc_hi, vcc_hi, 8
	s_add_u32 vcc_hi, vcc_hi, 0x400
	v_mov_b32_e32 v16, vcc_hi
	global_load_dword v16, v16, s[100:101] sc1
	s_waitcnt vmcnt(0)
	v_add_u32_e32 v15, v15, v0
	v_add_u32_e32 v15, v15, v1
	v_add_u32_e32 v15, v15, v2
	v_add_u32_e32 v15, v15, v3
	v_add_u32_e32 v15, v15, v4
	v_add_u32_e32 v15, v15, v5
	v_add_u32_e32 v15, v15, v6
	v_add_u32_e32 v15, v15, v7
	v_add_u32_e32 v15, v15, v8
	v_add_u32_e32 v15, v15, v9
	v_add_u32_e32 v15, v15, v10
	v_add_u32_e32 v15, v15, v11
	v_add_u32_e32 v15, v15, v12
	v_add_u32_e32 v15, v15, v13
	v_add_u32_e32 v15, v15, v14
	v_readfirstlane_b32 vcc_hi, v15
	v_readfirstlane_b32 s99, v16
	s_nop 3
	s_cmp_eq_u32 vcc_hi, vcc_lo
	s_cbranch_scc1 .Lhb0_cenok
	s_sleep 1
	s_sub_u32 m0, m0, 1
	s_cmp_lg_u32 m0, 0
	s_cbranch_scc1 .Lhb0_cen
.Lhb0_cenok:
	s_max_u32 s99, s99, 1
	v_mov_b32_e32 v15, 0x22fc0
	v_mov_b32_e32 v0, s99
	ds_write_b32 v15, v0 offset:4
	s_waitcnt lgkmcnt(0)
.Lhb0_have:
	v_readlane_b32 vcc_hi, v252, 10
	s_lshl_b32 vcc_hi, vcc_hi, 8
	s_add_u32 vcc_hi, vcc_hi, 0x1400
	s_mul_i32 vcc_lo, vcc_lo, s98
	v_mov_b32_e32 v15, vcc_hi
	v_mov_b32_e32 v0, 1
	global_atomic_add v0, v15, v0, s[100:101] sc0
	s_mul_i32 m0, s98, s99
	v_add_u32_e32 v15, 0x1000, v15
	s_waitcnt vmcnt(0)
	v_readfirstlane_b32 vcc_hi, v0
	s_nop 3
	s_add_u32 vcc_hi, vcc_hi, 1
	s_cmp_lg_u32 vcc_hi, m0
	s_cbranch_scc1 .Lhb0_poll
	buffer_wbl2 sc1
	v_mov_b32_e32 v0, s99
	v_mov_b32_e32 v16, 0x3400
	s_waitcnt vmcnt(0)
	global_atomic_add v0, v16, v0, s[100:101] sc0
	s_waitcnt vmcnt(0)
	v_readfirstlane_b32 vcc_hi, v0
	s_nop 3
	s_add_u32 vcc_hi, vcc_hi, s99
	s_cmp_lg_u32 vcc_hi, vcc_lo
	s_cbranch_scc1 .Lhb0_poll
	v_mov_b32_e32 v0, 1
	v_mov_b32_e32 v16, 0x2400
	global_atomic_add v16, v0, s[100:101]
	global_atomic_add v16, v0, s[100:101] offset:256
	global_atomic_add v16, v0, s[100:101] offset:512
	global_atomic_add v16, v0, s[100:101] offset:768
	global_atomic_add v16, v0, s[100:101] offset:1024
	global_atomic_add v16, v0, s[100:101] offset:1280
	global_atomic_add v16, v0, s[100:101] offset:1536
	global_atomic_add v16, v0, s[100:101] offset:1792
	global_atomic_add v16, v0, s[100:101] offset:2048
	global_atomic_add v16, v0, s[100:101] offset:2304
	global_atomic_add v16, v0, s[100:101] offset:2560
	global_atomic_add v16, v0, s[100:101] offset:2816
	global_atomic_add v16, v0, s[100:101] offset:3072
	global_atomic_add v16, v0, s[100:101] offset:3328
	global_atomic_add v16, v0, s[100:101] offset:3584
	global_atomic_add v16, v0, s[100:101] offset:3840
.Lhb0_poll:
	s_mov_b32 s99, 0x800
.Lhb0_spin:
	global_load_dword v0, v15, s[100:101] sc1
	s_waitcnt vmcnt(0)
	v_readfirstlane_b32 vcc_hi, v0
	s_nop 3
	s_cmp_ge_u32 vcc_hi, s98
	s_cbranch_scc1 .Lhb0_done
	s_sleep 1
	s_sub_u32 s99, s99, 1
	s_cmp_lg_u32 s99, 0
	s_cbranch_scc1 .Lhb0_spin
.Lhb0_done:
	buffer_inv sc1
	s_waitcnt vmcnt(0)
	s_branch .LBB0_324
	v_mov_b32_e32 v0, s16
	s_waitcnt vmcnt(0) expcnt(0) lgkmcnt(0)
	ds_read_b32 v2, v0
	v_mov_b32_e32 v0, s17
	ds_read_b32 v0, v0
	s_waitcnt lgkmcnt(1)
	v_cmp_ne_u32_e32 vcc, 0, v2
	s_cbranch_vccnz .LBB0_341
	s_mov_b32 s10, 1
	s_branch .LBB0_329

; __device__ __forceinline__ void xcd_barrier(const XcdBarrier& b) {
;     ...
;     if (threadIdx.x == 0) {
;         unsigned* bar = b.bar;
;         __builtin_amdgcn_s_waitcnt(0);
;         unsigned nloc = b.st[0], nx = b.st[1];
;         if (nloc == 0u) { xcd_barrier_complete(bar, b.x, nloc, nx); b.st[0] = nloc; b.st[1] = nx; }
.LBB0_401:
	s_waitcnt vmcnt(0)
	s_waitcnt vmcnt(0)
	s_barrier
	s_mov_b64 s[38:39], exec
	v_readlane_b32 s8, v252, 11
	v_readlane_b32 s9, v252, 12
	s_and_b64 s[8:9], s[38:39], s[8:9]
	s_mov_b64 exec, s[8:9]
	s_cbranch_execz .LBB0_400
	v_readlane_b32 s98, v252, 4
	v_readlane_b32 s99, v252, 5
	s_load_dword vcc_lo, s[98:99], 0xf8
	v_readlane_b32 s100, v252, 2
	v_readlane_b32 s101, v252, 3
	v_mov_b32_e32 v15, 0x22fc0
	ds_read_b32 v0, v15
	s_waitcnt lgkmcnt(0)
	v_add_u32_e32 v0, 1, v0
	ds_write_b32 v15, v0
	s_nop 0
	v_readfirstlane_b32 s98, v0
	ds_read_b32 v0, v15 offset:4
	s_waitcnt lgkmcnt(0)
	v_readfirstlane_b32 s99, v0
	s_mov_b32 m0, 0x400
	s_cmp_lg_u32 s99, 0
	s_cbranch_scc1 .Lhb1_have

; __device__ __forceinline__ unsigned xb_ld(unsigned* p)              { return __hip_atomic_load(p, __ATOMIC_RELAXED, __HIP_MEMORY_SCOPE_AGENT); }
; __device__ __forceinline__ unsigned xb_add(unsigned* p, unsigned v) { return __hip_atomic_fetch_add(p, v, __ATOMIC_RELAXED, __HIP_MEMORY_SCOPE_AGENT); }
; #define XB_SPIN(cond, bar) do { unsigned _sp = 0; while (cond) { __builtin_amdgcn_s_sleep(1); \
;     if ((++_sp & 255u) == 0u) { if (xb_ld(&(bar)[XB_TMO])) break; if (_sp > XB_SPIN_CAP) { atomicAdd(&(bar)[XB_TMO], 1u); break; } } } } while (0)
; __device__ __forceinline__ void xcd_barrier(const XcdBarrier& b) {
;     ...
;             __builtin_amdgcn_fence(__ATOMIC_ACQUIRE, "agent");
;             xb_add(&bar[XB_XGEN(b.x)], 1u);
;             asm volatile("s_waitcnt vmcnt(0)" ::: "memory");
;         } else {
;             XB_SPIN(xb_ld(&bar[XB_XGEN(b.x)]) == gen, bar);
;             __builtin_amdgcn_fence(__ATOMIC_ACQUIRE, "agent");
;             asm volatile("s_waitcnt vmcnt(0)" ::: "memory");
;         }
;     }
;     __syncthreads();
.Lhb1_done:
	buffer_inv sc1
	s_waitcnt vmcnt(0)
	s_branch .LBB0_400
	v_mov_b32_e32 v0, s16
	s_waitcnt vmcnt(0) expcnt(0) lgkmcnt(0)
	ds_read_b32 v2, v0
	v_mov_b32_e32 v0, s17
	ds_read_b32 v0, v0
	s_waitcnt lgkmcnt(1)
	v_cmp_ne_u32_e32 vcc, 0, v2
	s_cbranch_vccnz .LBB0_417
	s_mov_b32 s42, 1
	s_branch .LBB0_405

; __device__ __forceinline__ unsigned xb_ld(unsigned* p)              { return __hip_atomic_load(p, __ATOMIC_RELAXED, __HIP_MEMORY_SCOPE_AGENT); }
; __device__ __forceinline__ unsigned xb_add(unsigned* p, unsigned v) { return __hip_atomic_fetch_add(p, v, __ATOMIC_RELAXED, __HIP_MEMORY_SCOPE_AGENT); }
; #define XB_SPIN(cond, bar) do { unsigned _sp = 0; while (cond) { __builtin_amdgcn_s_sleep(1); \
;     if ((++_sp & 255u) == 0u) { if (xb_ld(&(bar)[XB_TMO])) break; if (_sp > XB_SPIN_CAP) { atomicAdd(&(bar)[XB_TMO], 1u); break; } } } } while (0)
; __device__ __forceinline__ void xcd_barrier_complete(unsigned* bar, unsigned x, unsigned& nloc, unsigned& nx) {
;     const unsigned G = gridDim.x * gridDim.y * gridDim.z;
;     unsigned sum, cnt, mine, sp = 0u;
;     for (;;) {
;         sum = 0u; cnt = 0u; mine = 0u;
; #pragma unroll
;         for (unsigned j = 0; j < 16; ++j) { const unsigned c = xb_ld(&bar[XB_XCNT(j)]); sum += c; cnt += (c > 0u) ? 1u : 0u; mine = (j == x) ? c : mine; }
;         if (sum == G) break;
;         __builtin_amdgcn_s_sleep(1);
;         if ((++sp & 255u) == 0u) { if (xb_ld(&bar[XB_TMO])) break; if (sp > XB_SPIN_CAP) { atomicAdd(&bar[XB_TMO], 1u); break; } }
;     }
;     nloc = mine > 0u ? mine : 1u; nx = cnt > 0u ? cnt : 1u;
; }
; __device__ __forceinline__ void xcd_barrier(const XcdBarrier& b) {
;     asm volatile("s_waitcnt vmcnt(0)" ::: "memory");
;     __syncthreads();
;     if (threadIdx.x == 0) {
;         unsigned* bar = b.bar;
;         __builtin_amdgcn_s_waitcnt(0);
;         unsigned nloc = b.st[0], nx = b.st[1];
;         if (nloc == 0u) { xcd_barrier_complete(bar, b.x, nloc, nx); b.st[0] = nloc; b.st[1] = nx; }
;         const unsigned old = xb_add(&bar[XB_XSUB(b.x)], 1u);
;         const unsigned gen = old / nloc;
;         if (old + 1u == (gen + 1u) * nloc) {
;             __builtin_amdgcn_fence(__ATOMIC_RELEASE, "agent");
;             asm volatile("s_waitcnt vmcnt(0)" ::: "memory");
;             const unsigned og = xb_add(&bar[XB_TOP], 1u);
;             const unsigned tg = og / nx;
;             if (og + 1u == (tg + 1u) * nx) xb_add(&bar[XB_TOPGEN], 1u);
;             else XB_SPIN(xb_ld(&bar[XB_TOPGEN]) == tg, bar);
;             __builtin_amdgcn_fence(__ATOMIC_ACQUIRE, "agent");
;             xb_add(&bar[XB_XGEN(b.x)], 1u);
.LBB0_788:
	s_waitcnt vmcnt(0)
	s_waitcnt vmcnt(0)
	s_barrier
	s_mov_b64 s[4:5], exec
	v_readlane_b32 s6, v252, 11
	v_readlane_b32 s7, v252, 12
	s_and_b64 s[6:7], s[4:5], s[6:7]
	s_mov_b64 exec, s[6:7]
	s_cbranch_execz .LBB0_787
	v_readlane_b32 s98, v252, 4
	v_readlane_b32 s99, v252, 5
	s_load_dword vcc_lo, s[98:99], 0xf8
	v_readlane_b32 s100, v252, 2
	v_readlane_b32 s101, v252, 3
	v_mov_b32_e32 v3, 0x22fc0
	ds_read_b32 v0, v3
	s_waitcnt lgkmcnt(0)
	v_add_u32_e32 v0, 1, v0
	ds_write_b32 v3, v0
	s_nop 0
	v_readfirstlane_b32 s98, v0
	ds_read_b32 v0, v3 offset:4
	s_waitcnt lgkmcnt(0)
	v_readfirstlane_b32 s99, v0
	s_mov_b32 m0, 0x400
	s_cmp_lg_u32 s99, 0
	s_cbranch_scc1 .Lhb2_have
.Lhb2_cen:
	v_mov_b32_e32 v16, 0x400
	global_load_dword v3, v16, s[100:101] sc1
	global_load_dword v0, v16, s[100:101] offset:256 sc1
	global_load_dword v1, v16, s[100:101] offset:512 sc1
	global_load_dword v2, v16, s[100:101] offset:768 sc1
	global_load_dword v4, v16, s[100:101] offset:1024 sc1
	global_load_dword v5, v16, s[100:101] offset:1280 sc1
	global_load_dword v6, v16, s[100:101] offset:1536 sc1
	global_load_dword v7, v16, s[100:101] offset:1792 sc1
	global_load_dword v8, v16, s[100:101] offset:2048 sc1
	global_load_dword v9, v16, s[100:101] offset:2304 sc1
	global_load_dword v10, v16, s[100:101] offset:2560 sc1
	global_load_dword v11, v16, s[100:101] offset:2816 sc1
	global_load_dword v12, v16, s[100:101] offset:3072 sc1
	global_load_dword v13, v16, s[100:101] offset:3328 sc1
	global_load_dword v14, v16, s[100:101] offset:3584 sc1
	global_load_dword v15, v16, s[100:101] offset:3840 sc1
	v_readlane_b32 vcc_hi, v252, 10
	s_lshl_b32 vcc_hi, vcc_hi, 8
	s_add_u32 vcc_hi, vcc_hi, 0x400
	v_mov_b32_e32 v16, vcc_hi
	global_load_dword v16, v16, s[100:101] sc1
	s_waitcnt vmcnt(0)
	v_add_u32_e32 v3, v3, v0
	v_add_u32_e32 v3, v3, v1
	v_add_u32_e32 v3, v3, v2
	v_add_u32_e32 v3, v3, v4
	v_add_u32_e32 v3, v3, v5
	v_add_u32_e32 v3, v3, v6
	v_add_u32_e32 v3, v3, v7
	v_add_u32_e32 v3, v3, v8
	v_add_u32_e32 v3, v3, v9
	v_add_u32_e32 v3, v3, v10
	v_add_u32_e32 v3, v3, v11
	v_add_u32_e32 v3, v3, v12
	v_add_u32_e32 v3, v3, v13
	v_add_u32_e32 v3, v3, v14
	v_add_u32_e32 v3, v3, v15
	v_readfirstlane_b32 vcc_hi, v3
	v_readfirstlane_b32 s99, v16
	s_nop 3
	s_cmp_eq_u32 vcc_hi, vcc_lo
	s_cbranch_scc1 .Lhb2_cenok
	s_sleep 1
	s_sub_u32 m0, m0, 1
	s_cmp_lg_u32 m0, 0
	s_cbranch_scc1 .Lhb2_cen
.Lhb2_cenok:
	s_max_u32 s99, s99, 1
	v_mov_b32_e32 v3, 0x22fc0
	v_mov_b32_e32 v0, s99
	ds_write_b32 v3, v0 offset:4
	s_waitcnt lgkmcnt(0)
.Lhb2_have:
	v_readlane_b32 vcc_hi, v252, 10
	s_lshl_b32 vcc_hi, vcc_hi, 8
	s_add_u32 vcc_hi, vcc_hi, 0x1400
	s_mul_i32 vcc_lo, vcc_lo, s98
	v_mov_b32_e32 v3, vcc_hi
	v_mov_b32_e32 v0, 1
	global_atomic_add v0, v3, v0, s[100:101] sc0
	s_mul_i32 m0, s98, s99
	v_add_u32_e32 v3, 0x1000, v3
	s_waitcnt vmcnt(0)
	v_readfirstlane_b32 vcc_hi, v0
	s_nop 3
	s_add_u32 vcc_hi, vcc_hi, 1
	s_cmp_lg_u32 vcc_hi, m0
	s_cbranch_scc1 .Lhb2_poll
	buffer_wbl2 sc1
	v_mov_b32_e32 v0, s99
	v_mov_b32_e32 v16, 0x3400
	s_waitcnt vmcnt(0)
	global_atomic_add v0, v16, v0, s[100:101] sc0
	s_waitcnt vmcnt(0)
	v_readfirstlane_b32 vcc_hi, v0
	s_nop 3
	s_add_u32 vcc_hi, vcc_hi, s99
	s_cmp_lg_u32 vcc_hi, vcc_lo
	s_cbranch_scc1 .Lhb2_poll
	v_mov_b32_e32 v0, 1
	v_mov_b32_e32 v16, 0x2400
	global_atomic_add v16, v0, s[100:101]
	global_atomic_add v16, v0, s[100:101] offset:256
	global_atomic_add v16, v0, s[100:101] offset:512
	global_atomic_add v16, v0, s[100:101] offset:768
	global_atomic_add v16, v0, s[100:101] offset:1024
	global_atomic_add v16, v0, s[100:101] offset:1280
	global_atomic_add v16, v0, s[100:101] offset:1536
	global_atomic_add v16, v0, s[100:101] offset:1792
	global_atomic_add v16, v0, s[100:101] offset:2048
	global_atomic_add v16, v0, s[100:101] offset:2304
	global_atomic_add v16, v0, s[100:101] offset:2560
	global_atomic_add v16, v0, s[100:101] offset:2816
	global_atomic_add v16, v0, s[100:101] offset:3072
	global_atomic_add v16, v0, s[100:101] offset:3328
	global_atomic_add v16, v0, s[100:101] offset:3584
	global_atomic_add v16, v0, s[100:101] offset:3840

; __device__ __forceinline__ unsigned xb_ld(unsigned* p)              { return __hip_atomic_load(p, __ATOMIC_RELAXED, __HIP_MEMORY_SCOPE_AGENT); }
; __device__ __forceinline__ unsigned xb_add(unsigned* p, unsigned v) { return __hip_atomic_fetch_add(p, v, __ATOMIC_RELAXED, __HIP_MEMORY_SCOPE_AGENT); }
; #define XB_SPIN(cond, bar) do { unsigned _sp = 0; while (cond) { __builtin_amdgcn_s_sleep(1); \
;     if ((++_sp & 255u) == 0u) { if (xb_ld(&(bar)[XB_TMO])) break; if (_sp > XB_SPIN_CAP) { atomicAdd(&(bar)[XB_TMO], 1u); break; } } } } while (0)
; __device__ __forceinline__ void xcd_barrier(const XcdBarrier& b) {
;     ...
;             else XB_SPIN(xb_ld(&bar[XB_TOPGEN]) == tg, bar);
;             __builtin_amdgcn_fence(__ATOMIC_ACQUIRE, "agent");
;             xb_add(&bar[XB_XGEN(b.x)], 1u);
;             asm volatile("s_waitcnt vmcnt(0)" ::: "memory");
;         } else {
;             XB_SPIN(xb_ld(&bar[XB_XGEN(b.x)]) == gen, bar);
;             __builtin_amdgcn_fence(__ATOMIC_ACQUIRE, "agent");
;             asm volatile("s_waitcnt vmcnt(0)" ::: "memory");
;         }
;     }
;     __syncthreads();
.Lhb2_spin:
	global_load_dword v0, v3, s[100:101] sc1
	s_waitcnt vmcnt(0)
	v_readfirstlane_b32 vcc_hi, v0
	s_nop 3
	s_cmp_ge_u32 vcc_hi, s98
	s_cbranch_scc1 .Lhb2_done
	s_sleep 1
	s_sub_u32 s99, s99, 1
	s_cmp_lg_u32 s99, 0
	s_cbranch_scc1 .Lhb2_spin
.Lhb2_done:
	buffer_inv sc1
	s_waitcnt vmcnt(0)
	s_branch .LBB0_787
	v_readlane_b32 s6, v255, 41
	s_waitcnt vmcnt(0) expcnt(0) lgkmcnt(0)
	s_nop 0
	v_mov_b32_e32 v0, s6
	ds_read_b32 v2, v0
	v_readlane_b32 s6, v255, 42
	s_waitcnt lgkmcnt(0)
	v_cmp_ne_u32_e32 vcc, 0, v2
	v_mov_b32_e32 v0, s6
	ds_read_b32 v0, v0
	s_cbranch_vccnz .LBB0_804
	s_mov_b32 s18, 1
	s_branch .LBB0_792

; __device__ __forceinline__ void xcd_barrier(const XcdBarrier& b) {
;     ...
;     if (threadIdx.x == 0) {
;         unsigned* bar = b.bar;
;         __builtin_amdgcn_s_waitcnt(0);
;         unsigned nloc = b.st[0], nx = b.st[1];
;         if (nloc == 0u) { xcd_barrier_complete(bar, b.x, nloc, nx); b.st[0] = nloc; b.st[1] = nx; }
.LBB0_855:
	s_waitcnt vmcnt(0)
	s_waitcnt vmcnt(0)
	s_barrier
	s_mov_b64 s[92:93], exec
	v_readlane_b32 s4, v252, 11
	v_readlane_b32 s5, v252, 12
	s_and_b64 s[4:5], s[92:93], s[4:5]
	s_mov_b64 exec, s[4:5]
	s_cbranch_execz .LBB0_854
	v_readlane_b32 s98, v252, 4
	v_readlane_b32 s99, v252, 5
	s_load_dword vcc_lo, s[98:99], 0xf8
	v_readlane_b32 s100, v252, 2
	v_readlane_b32 s101, v252, 3
	v_mov_b32_e32 v15, 0x22fc0
	ds_read_b32 v0, v15
	s_waitcnt lgkmcnt(0)
	v_add_u32_e32 v0, 1, v0
	ds_write_b32 v15, v0
	s_nop 0
	v_readfirstlane_b32 s98, v0
	ds_read_b32 v0, v15 offset:4
	s_waitcnt lgkmcnt(0)
	v_readfirstlane_b32 s99, v0
	s_mov_b32 m0, 0x400
	s_cmp_lg_u32 s99, 0
	s_cbranch_scc1 .Lhb3_have

; __device__ __forceinline__ unsigned xb_ld(unsigned* p)              { return __hip_atomic_load(p, __ATOMIC_RELAXED, __HIP_MEMORY_SCOPE_AGENT); }
; __device__ __forceinline__ unsigned xb_add(unsigned* p, unsigned v) { return __hip_atomic_fetch_add(p, v, __ATOMIC_RELAXED, __HIP_MEMORY_SCOPE_AGENT); }
; #define XB_SPIN(cond, bar) do { unsigned _sp = 0; while (cond) { __builtin_amdgcn_s_sleep(1); \
;     if ((++_sp & 255u) == 0u) { if (xb_ld(&(bar)[XB_TMO])) break; if (_sp > XB_SPIN_CAP) { atomicAdd(&(bar)[XB_TMO], 1u); break; } } } } while (0)
; __device__ __forceinline__ void xcd_barrier(const XcdBarrier& b) {
;     ...
;             __builtin_amdgcn_fence(__ATOMIC_ACQUIRE, "agent");
;             xb_add(&bar[XB_XGEN(b.x)], 1u);
;             asm volatile("s_waitcnt vmcnt(0)" ::: "memory");
;         } else {
;             XB_SPIN(xb_ld(&bar[XB_XGEN(b.x)]) == gen, bar);
;             __builtin_amdgcn_fence(__ATOMIC_ACQUIRE, "agent");
;             asm volatile("s_waitcnt vmcnt(0)" ::: "memory");
;         }
;     }
;     __syncthreads();
.Lhb3_done:
	buffer_inv sc1
	s_waitcnt vmcnt(0)
	s_branch .LBB0_854
	v_mov_b32_e32 v0, s39
	s_waitcnt vmcnt(0) expcnt(0) lgkmcnt(0)
	ds_read_b32 v2, v0
	v_mov_b32_e32 v0, s14
	ds_read_b32 v0, v0
	s_waitcnt lgkmcnt(1)
	v_cmp_ne_u32_e32 vcc, 0, v2
	s_cbranch_vccnz .LBB0_871
	s_mov_b32 s8, 1
	s_branch .LBB0_859

; __device__ __forceinline__ unsigned xb_ld(unsigned* p)              { return __hip_atomic_load(p, __ATOMIC_RELAXED, __HIP_MEMORY_SCOPE_AGENT); }
; __device__ __forceinline__ unsigned xb_add(unsigned* p, unsigned v) { return __hip_atomic_fetch_add(p, v, __ATOMIC_RELAXED, __HIP_MEMORY_SCOPE_AGENT); }
; #define XB_SPIN(cond, bar) do { unsigned _sp = 0; while (cond) { __builtin_amdgcn_s_sleep(1); \
;     if ((++_sp & 255u) == 0u) { if (xb_ld(&(bar)[XB_TMO])) break; if (_sp > XB_SPIN_CAP) { atomicAdd(&(bar)[XB_TMO], 1u); break; } } } } while (0)
; __device__ __forceinline__ void xcd_barrier_complete(unsigned* bar, unsigned x, unsigned& nloc, unsigned& nx) {
;     const unsigned G = gridDim.x * gridDim.y * gridDim.z;
;     unsigned sum, cnt, mine, sp = 0u;
;     for (;;) {
;         sum = 0u; cnt = 0u; mine = 0u;
; #pragma unroll
;         for (unsigned j = 0; j < 16; ++j) { const unsigned c = xb_ld(&bar[XB_XCNT(j)]); sum += c; cnt += (c > 0u) ? 1u : 0u; mine = (j == x) ? c : mine; }
;         if (sum == G) break;
;         __builtin_amdgcn_s_sleep(1);
;         if ((++sp & 255u) == 0u) { if (xb_ld(&bar[XB_TMO])) break; if (sp > XB_SPIN_CAP) { atomicAdd(&bar[XB_TMO], 1u); break; } }
;     }
;     nloc = mine > 0u ? mine : 1u; nx = cnt > 0u ? cnt : 1u;
; }
; __device__ __forceinline__ void xcd_barrier(const XcdBarrier& b) {
;     asm volatile("s_waitcnt vmcnt(0)" ::: "memory");
;     __syncthreads();
;     if (threadIdx.x == 0) {
;         unsigned* bar = b.bar;
;         __builtin_amdgcn_s_waitcnt(0);
;         unsigned nloc = b.st[0], nx = b.st[1];
;         if (nloc == 0u) { xcd_barrier_complete(bar, b.x, nloc, nx); b.st[0] = nloc; b.st[1] = nx; }
;         const unsigned old = xb_add(&bar[XB_XSUB(b.x)], 1u);
;         const unsigned gen = old / nloc;
;         if (old + 1u == (gen + 1u) * nloc) {
;             __builtin_amdgcn_fence(__ATOMIC_RELEASE, "agent");
;             asm volatile("s_waitcnt vmcnt(0)" ::: "memory");
;             const unsigned og = xb_add(&bar[XB_TOP], 1u);
;             const unsigned tg = og / nx;
;             if (og + 1u == (tg + 1u) * nx) xb_add(&bar[XB_TOPGEN], 1u);
;             else XB_SPIN(xb_ld(&bar[XB_TOPGEN]) == tg, bar);
;             __builtin_amdgcn_fence(__ATOMIC_ACQUIRE, "agent");
;             xb_add(&bar[XB_XGEN(b.x)], 1u);
.LBB0_948:
	s_waitcnt vmcnt(0)
	s_waitcnt vmcnt(0) lgkmcnt(0)
	s_barrier
	s_mov_b64 s[4:5], exec
	v_readlane_b32 s6, v252, 11
	v_readlane_b32 s7, v252, 12
	s_and_b64 s[6:7], s[4:5], s[6:7]
	s_mov_b64 exec, s[6:7]
	s_cbranch_execz .LBB0_947
	v_readlane_b32 s98, v252, 4
	v_readlane_b32 s99, v252, 5
	s_load_dword vcc_lo, s[98:99], 0xf8
	v_readlane_b32 s100, v252, 2
	v_readlane_b32 s101, v252, 3
	v_mov_b32_e32 v16, 0x22fc0
	ds_read_b32 v1, v16
	s_waitcnt lgkmcnt(0)
	v_add_u32_e32 v1, 1, v1
	ds_write_b32 v16, v1
	s_nop 0
	v_readfirstlane_b32 s98, v1
	ds_read_b32 v1, v16 offset:4
	s_waitcnt lgkmcnt(0)
	v_readfirstlane_b32 s99, v1
	s_mov_b32 m0, 0x400
	s_cmp_lg_u32 s99, 0
	s_cbranch_scc1 .Lhb4_have
.Lhb4_cen:
	v_mov_b32_e32 v17, 0x400
	global_load_dword v16, v17, s[100:101] sc1
	global_load_dword v1, v17, s[100:101] offset:256 sc1
	global_load_dword v2, v17, s[100:101] offset:512 sc1
	global_load_dword v3, v17, s[100:101] offset:768 sc1
	global_load_dword v4, v17, s[100:101] offset:1024 sc1
	global_load_dword v5, v17, s[100:101] offset:1280 sc1
	global_load_dword v6, v17, s[100:101] offset:1536 sc1
	global_load_dword v7, v17, s[100:101] offset:1792 sc1
	global_load_dword v8, v17, s[100:101] offset:2048 sc1
	global_load_dword v9, v17, s[100:101] offset:2304 sc1
	global_load_dword v10, v17, s[100:101] offset:2560 sc1
	global_load_dword v11, v17, s[100:101] offset:2816 sc1
	global_load_dword v12, v17, s[100:101] offset:3072 sc1
	global_load_dword v13, v17, s[100:101] offset:3328 sc1
	global_load_dword v14, v17, s[100:101] offset:3584 sc1
	global_load_dword v15, v17, s[100:101] offset:3840 sc1
	v_readlane_b32 vcc_hi, v252, 10
	s_lshl_b32 vcc_hi, vcc_hi, 8
	s_add_u32 vcc_hi, vcc_hi, 0x400
	v_mov_b32_e32 v17, vcc_hi
	global_load_dword v17, v17, s[100:101] sc1
	s_waitcnt vmcnt(0)
	v_add_u32_e32 v16, v16, v1
	v_add_u32_e32 v16, v16, v2
	v_add_u32_e32 v16, v16, v3
	v_add_u32_e32 v16, v16, v4
	v_add_u32_e32 v16, v16, v5
	v_add_u32_e32 v16, v16, v6
	v_add_u32_e32 v16, v16, v7
	v_add_u32_e32 v16, v16, v8
	v_add_u32_e32 v16, v16, v9
	v_add_u32_e32 v16, v16, v10
	v_add_u32_e32 v16, v16, v11
	v_add_u32_e32 v16, v16, v12
	v_add_u32_e32 v16, v16, v13
	v_add_u32_e32 v16, v16, v14
	v_add_u32_e32 v16, v16, v15
	v_readfirstlane_b32 vcc_hi, v16
	v_readfirstlane_b32 s99, v17
	s_nop 3
	s_cmp_eq_u32 vcc_hi, vcc_lo
	s_cbranch_scc1 .Lhb4_cenok
	s_sleep 1
	s_sub_u32 m0, m0, 1
	s_cmp_lg_u32 m0, 0
	s_cbranch_scc1 .Lhb4_cen
.Lhb4_cenok:
	s_max_u32 s99, s99, 1
	v_mov_b32_e32 v16, 0x22fc0
	v_mov_b32_e32 v1, s99
	ds_write_b32 v16, v1 offset:4
	s_waitcnt lgkmcnt(0)
.Lhb4_have:
	v_readlane_b32 vcc_hi, v252, 10
	s_lshl_b32 vcc_hi, vcc_hi, 8
	s_add_u32 vcc_hi, vcc_hi, 0x1400
	s_mul_i32 vcc_lo, vcc_lo, s98
	v_mov_b32_e32 v16, vcc_hi
	v_mov_b32_e32 v1, 1
	global_atomic_add v1, v16, v1, s[100:101] sc0
	s_mul_i32 m0, s98, s99
	v_add_u32_e32 v16, 0x1000, v16
	s_waitcnt vmcnt(0)
	v_readfirstlane_b32 vcc_hi, v1
	s_nop 3
	s_add_u32 vcc_hi, vcc_hi, 1
	s_cmp_lg_u32 vcc_hi, m0
	s_cbranch_scc1 .Lhb4_poll
	buffer_wbl2 sc1
	v_mov_b32_e32 v1, s99
	v_mov_b32_e32 v17, 0x3400
	s_waitcnt vmcnt(0)
	global_atomic_add v1, v17, v1, s[100:101] sc0
	s_waitcnt vmcnt(0)
	v_readfirstlane_b32 vcc_hi, v1
	s_nop 3
	s_add_u32 vcc_hi, vcc_hi, s99
	s_cmp_lg_u32 vcc_hi, vcc_lo
	s_cbranch_scc1 .Lhb4_poll
	v_mov_b32_e32 v1, 1
	v_mov_b32_e32 v17, 0x2400
	global_atomic_add v17, v1, s[100:101]
	global_atomic_add v17, v1, s[100:101] offset:256
	global_atomic_add v17, v1, s[100:101] offset:512
	global_atomic_add v17, v1, s[100:101] offset:768
	global_atomic_add v17, v1, s[100:101] offset:1024
	global_atomic_add v17, v1, s[100:101] offset:1280
	global_atomic_add v17, v1, s[100:101] offset:1536
	global_atomic_add v17, v1, s[100:101] offset:1792
	global_atomic_add v17, v1, s[100:101] offset:2048
	global_atomic_add v17, v1, s[100:101] offset:2304
	global_atomic_add v17, v1, s[100:101] offset:2560
	global_atomic_add v17, v1, s[100:101] offset:2816
	global_atomic_add v17, v1, s[100:101] offset:3072
	global_atomic_add v17, v1, s[100:101] offset:3328
	global_atomic_add v17, v1, s[100:101] offset:3584
	global_atomic_add v17, v1, s[100:101] offset:3840

; __device__ __forceinline__ unsigned xb_ld(unsigned* p)              { return __hip_atomic_load(p, __ATOMIC_RELAXED, __HIP_MEMORY_SCOPE_AGENT); }
; __device__ __forceinline__ unsigned xb_add(unsigned* p, unsigned v) { return __hip_atomic_fetch_add(p, v, __ATOMIC_RELAXED, __HIP_MEMORY_SCOPE_AGENT); }
; #define XB_SPIN(cond, bar) do { unsigned _sp = 0; while (cond) { __builtin_amdgcn_s_sleep(1); \
;     if ((++_sp & 255u) == 0u) { if (xb_ld(&(bar)[XB_TMO])) break; if (_sp > XB_SPIN_CAP) { atomicAdd(&(bar)[XB_TMO], 1u); break; } } } } while (0)
; __device__ __forceinline__ void xcd_barrier(const XcdBarrier& b) {
;     ...
;             else XB_SPIN(xb_ld(&bar[XB_TOPGEN]) == tg, bar);
;             __builtin_amdgcn_fence(__ATOMIC_ACQUIRE, "agent");
;             xb_add(&bar[XB_XGEN(b.x)], 1u);
;             asm volatile("s_waitcnt vmcnt(0)" ::: "memory");
;         } else {
;             XB_SPIN(xb_ld(&bar[XB_XGEN(b.x)]) == gen, bar);
;             __builtin_amdgcn_fence(__ATOMIC_ACQUIRE, "agent");
;             asm volatile("s_waitcnt vmcnt(0)" ::: "memory");
;         }
;     }
;     __syncthreads();
.Lhb4_spin:
	global_load_dword v1, v16, s[100:101] sc1
	s_waitcnt vmcnt(0)
	v_readfirstlane_b32 vcc_hi, v1
	s_nop 3
	s_cmp_ge_u32 vcc_hi, s98
	s_cbranch_scc1 .Lhb4_done
	s_sleep 1
	s_sub_u32 s99, s99, 1
	s_cmp_lg_u32 s99, 0
	s_cbranch_scc1 .Lhb4_spin
.Lhb4_done:
	buffer_inv sc1
	s_waitcnt vmcnt(0)
	s_branch .LBB0_947
	v_mov_b32_e32 v1, s18
	s_waitcnt vmcnt(0) expcnt(0) lgkmcnt(0)
	ds_read_b32 v3, v1
	v_mov_b32_e32 v1, s19
	ds_read_b32 v2, v1
	s_waitcnt lgkmcnt(1)
	v_cmp_ne_u32_e32 vcc, 0, v3
	s_cbranch_vccnz .LBB0_964
	s_mov_b32 s20, 1
	s_branch .LBB0_952

; __device__ __forceinline__ void xcd_barrier(const XcdBarrier& b) {
;     ...
;     if (threadIdx.x == 0) {
;         unsigned* bar = b.bar;
;         __builtin_amdgcn_s_waitcnt(0);
;         unsigned nloc = b.st[0], nx = b.st[1];
;         if (nloc == 0u) { xcd_barrier_complete(bar, b.x, nloc, nx); b.st[0] = nloc; b.st[1] = nx; }
.LBB0_1050:
	s_waitcnt vmcnt(0)
	s_waitcnt vmcnt(0) lgkmcnt(0)
	s_barrier
	s_mov_b64 s[4:5], exec
	v_readlane_b32 s6, v252, 11
	v_readlane_b32 s7, v252, 12
	s_and_b64 s[6:7], s[4:5], s[6:7]
	s_mov_b64 exec, s[6:7]
	s_cbranch_execz .LBB0_1049
	v_readlane_b32 s98, v252, 4
	v_readlane_b32 s99, v252, 5
	s_load_dword vcc_lo, s[98:99], 0xf8
	v_readlane_b32 s100, v252, 2
	v_readlane_b32 s101, v252, 3
	v_mov_b32_e32 v15, 0x22fc0
	ds_read_b32 v0, v15
	s_waitcnt lgkmcnt(0)
	v_add_u32_e32 v0, 1, v0
	ds_write_b32 v15, v0
	s_nop 0
	v_readfirstlane_b32 s98, v0
	ds_read_b32 v0, v15 offset:4
	s_waitcnt lgkmcnt(0)
	v_readfirstlane_b32 s99, v0
	s_mov_b32 m0, 0x400
	s_cmp_lg_u32 s99, 0
	s_cbranch_scc1 .Lhb5_have

; __device__ __forceinline__ unsigned xb_ld(unsigned* p)              { return __hip_atomic_load(p, __ATOMIC_RELAXED, __HIP_MEMORY_SCOPE_AGENT); }
; __device__ __forceinline__ unsigned xb_add(unsigned* p, unsigned v) { return __hip_atomic_fetch_add(p, v, __ATOMIC_RELAXED, __HIP_MEMORY_SCOPE_AGENT); }
; #define XB_SPIN(cond, bar) do { unsigned _sp = 0; while (cond) { __builtin_amdgcn_s_sleep(1); \
;     if ((++_sp & 255u) == 0u) { if (xb_ld(&(bar)[XB_TMO])) break; if (_sp > XB_SPIN_CAP) { atomicAdd(&(bar)[XB_TMO], 1u); break; } } } } while (0)
; __device__ __forceinline__ void xcd_barrier(const XcdBarrier& b) {
;     ...
;             __builtin_amdgcn_fence(__ATOMIC_ACQUIRE, "agent");
;             xb_add(&bar[XB_XGEN(b.x)], 1u);
;             asm volatile("s_waitcnt vmcnt(0)" ::: "memory");
;         } else {
;             XB_SPIN(xb_ld(&bar[XB_XGEN(b.x)]) == gen, bar);
;             __builtin_amdgcn_fence(__ATOMIC_ACQUIRE, "agent");
;             asm volatile("s_waitcnt vmcnt(0)" ::: "memory");
;         }
;     }
;     __syncthreads();
.Lhb5_done:
	buffer_inv sc1
	s_waitcnt vmcnt(0)
	s_branch .LBB0_1049
	v_readlane_b32 s6, v252, 60
	s_waitcnt vmcnt(0) expcnt(0) lgkmcnt(0)
	s_nop 0
	v_mov_b32_e32 v0, s6
	ds_read_b32 v2, v0
	v_readlane_b32 s6, v252, 14
	s_waitcnt lgkmcnt(0)
	v_cmp_ne_u32_e32 vcc, 0, v2
	v_mov_b32_e32 v0, s6
	ds_read_b32 v0, v0
	s_cbranch_vccnz .LBB0_1066
	s_mov_b32 s14, 1
	s_branch .LBB0_1054

; __device__ __forceinline__ void xcd_barrier(const XcdBarrier& b) {
;     ...
;     if (threadIdx.x == 0) {
;         unsigned* bar = b.bar;
;         __builtin_amdgcn_s_waitcnt(0);
;         unsigned nloc = b.st[0], nx = b.st[1];
;         if (nloc == 0u) { xcd_barrier_complete(bar, b.x, nloc, nx); b.st[0] = nloc; b.st[1] = nx; }
.LBB0_1128:
	s_waitcnt vmcnt(0)
	s_waitcnt vmcnt(0) lgkmcnt(0)
	s_barrier
	s_mov_b64 s[38:39], exec
	v_readlane_b32 s4, v252, 11
	v_readlane_b32 s5, v252, 12
	s_and_b64 s[4:5], s[38:39], s[4:5]
	s_mov_b64 exec, s[4:5]
	s_cbranch_execz .LBB0_1127
	v_readlane_b32 s98, v252, 4
	v_readlane_b32 s99, v252, 5
	s_load_dword vcc_lo, s[98:99], 0xf8
	v_readlane_b32 s100, v252, 2
	v_readlane_b32 s101, v252, 3
	v_mov_b32_e32 v15, 0x22fc0
	ds_read_b32 v0, v15
	s_waitcnt lgkmcnt(0)
	v_add_u32_e32 v0, 1, v0
	ds_write_b32 v15, v0
	s_nop 0
	v_readfirstlane_b32 s98, v0
	ds_read_b32 v0, v15 offset:4
	s_waitcnt lgkmcnt(0)
	v_readfirstlane_b32 s99, v0
	s_mov_b32 m0, 0x400
	s_cmp_lg_u32 s99, 0
	s_cbranch_scc1 .Lhb6_have

; __device__ __forceinline__ unsigned xb_ld(unsigned* p)              { return __hip_atomic_load(p, __ATOMIC_RELAXED, __HIP_MEMORY_SCOPE_AGENT); }
; __device__ __forceinline__ unsigned xb_add(unsigned* p, unsigned v) { return __hip_atomic_fetch_add(p, v, __ATOMIC_RELAXED, __HIP_MEMORY_SCOPE_AGENT); }
; #define XB_SPIN(cond, bar) do { unsigned _sp = 0; while (cond) { __builtin_amdgcn_s_sleep(1); \
;     if ((++_sp & 255u) == 0u) { if (xb_ld(&(bar)[XB_TMO])) break; if (_sp > XB_SPIN_CAP) { atomicAdd(&(bar)[XB_TMO], 1u); break; } } } } while (0)
; __device__ __forceinline__ void xcd_barrier(const XcdBarrier& b) {
;     ...
;             __builtin_amdgcn_fence(__ATOMIC_ACQUIRE, "agent");
;             xb_add(&bar[XB_XGEN(b.x)], 1u);
;             asm volatile("s_waitcnt vmcnt(0)" ::: "memory");
;         } else {
;             XB_SPIN(xb_ld(&bar[XB_XGEN(b.x)]) == gen, bar);
;             __builtin_amdgcn_fence(__ATOMIC_ACQUIRE, "agent");
;             asm volatile("s_waitcnt vmcnt(0)" ::: "memory");
;         }
;     }
;     __syncthreads();
.Lhb6_done:
	buffer_inv sc1
	s_waitcnt vmcnt(0)
	s_branch .LBB0_1127
	v_mov_b32_e32 v0, s41
	s_waitcnt vmcnt(0) expcnt(0) lgkmcnt(0)
	ds_read_b32 v2, v0
	v_mov_b32_e32 v0, s14
	ds_read_b32 v0, v0
	s_waitcnt lgkmcnt(1)
	v_cmp_ne_u32_e32 vcc, 0, v2
	s_cbranch_vccnz .LBB0_1144
	s_mov_b32 s16, 1
	s_branch .LBB0_1132

; __device__ __forceinline__ unsigned xb_ld(unsigned* p)              { return __hip_atomic_load(p, __ATOMIC_RELAXED, __HIP_MEMORY_SCOPE_AGENT); }
; __device__ __forceinline__ unsigned xb_add(unsigned* p, unsigned v) { return __hip_atomic_fetch_add(p, v, __ATOMIC_RELAXED, __HIP_MEMORY_SCOPE_AGENT); }
; #define XB_SPIN(cond, bar) do { unsigned _sp = 0; while (cond) { __builtin_amdgcn_s_sleep(1); \
;     if ((++_sp & 255u) == 0u) { if (xb_ld(&(bar)[XB_TMO])) break; if (_sp > XB_SPIN_CAP) { atomicAdd(&(bar)[XB_TMO], 1u); break; } } } } while (0)
; __device__ __forceinline__ void xcd_barrier_complete(unsigned* bar, unsigned x, unsigned& nloc, unsigned& nx) {
;     const unsigned G = gridDim.x * gridDim.y * gridDim.z;
;     unsigned sum, cnt, mine, sp = 0u;
;     for (;;) {
;         sum = 0u; cnt = 0u; mine = 0u;
; #pragma unroll
;         for (unsigned j = 0; j < 16; ++j) { const unsigned c = xb_ld(&bar[XB_XCNT(j)]); sum += c; cnt += (c > 0u) ? 1u : 0u; mine = (j == x) ? c : mine; }
;         if (sum == G) break;
;         __builtin_amdgcn_s_sleep(1);
;         if ((++sp & 255u) == 0u) { if (xb_ld(&bar[XB_TMO])) break; if (sp > XB_SPIN_CAP) { atomicAdd(&bar[XB_TMO], 1u); break; } }
;     }
;     nloc = mine > 0u ? mine : 1u; nx = cnt > 0u ? cnt : 1u;
; }
; __device__ __forceinline__ void xcd_barrier(const XcdBarrier& b) {
;     asm volatile("s_waitcnt vmcnt(0)" ::: "memory");
;     __syncthreads();
;     if (threadIdx.x == 0) {
;         unsigned* bar = b.bar;
;         __builtin_amdgcn_s_waitcnt(0);
;         unsigned nloc = b.st[0], nx = b.st[1];
;         if (nloc == 0u) { xcd_barrier_complete(bar, b.x, nloc, nx); b.st[0] = nloc; b.st[1] = nx; }
;         const unsigned old = xb_add(&bar[XB_XSUB(b.x)], 1u);
;         const unsigned gen = old / nloc;
;         if (old + 1u == (gen + 1u) * nloc) {
;             __builtin_amdgcn_fence(__ATOMIC_RELEASE, "agent");
;             asm volatile("s_waitcnt vmcnt(0)" ::: "memory");
;             const unsigned og = xb_add(&bar[XB_TOP], 1u);
;             const unsigned tg = og / nx;
;             if (og + 1u == (tg + 1u) * nx) xb_add(&bar[XB_TOPGEN], 1u);
;             else XB_SPIN(xb_ld(&bar[XB_TOPGEN]) == tg, bar);
;             __builtin_amdgcn_fence(__ATOMIC_ACQUIRE, "agent");
;             xb_add(&bar[XB_XGEN(b.x)], 1u);
.LBB0_1237:
	s_waitcnt vmcnt(0)
	s_waitcnt vmcnt(0)
	s_barrier
	s_mov_b64 s[84:85], exec
	v_readlane_b32 s6, v252, 11
	v_readlane_b32 s7, v252, 12
	s_and_b64 s[6:7], s[84:85], s[6:7]
	s_mov_b64 exec, s[6:7]
	s_cbranch_execz .LBB0_1236
	v_readlane_b32 s98, v252, 4
	v_readlane_b32 s99, v252, 5
	s_load_dword vcc_lo, s[98:99], 0xf8
	v_readlane_b32 s100, v252, 2
	v_readlane_b32 s101, v252, 3
	v_mov_b32_e32 v17, 0x22fc0
	ds_read_b32 v0, v17
	s_waitcnt lgkmcnt(0)
	v_add_u32_e32 v0, 1, v0
	ds_write_b32 v17, v0
	s_nop 0
	v_readfirstlane_b32 s98, v0
	ds_read_b32 v0, v17 offset:4
	s_waitcnt lgkmcnt(0)
	v_readfirstlane_b32 s99, v0
	s_mov_b32 m0, 0x400
	s_cmp_lg_u32 s99, 0
	s_cbranch_scc1 .Lhb7_have
.Lhb7_cen:
	v_mov_b32_e32 v18, 0x400
	global_load_dword v17, v18, s[100:101] sc1
	global_load_dword v0, v18, s[100:101] offset:256 sc1
	global_load_dword v1, v18, s[100:101] offset:512 sc1
	global_load_dword v4, v18, s[100:101] offset:768 sc1
	global_load_dword v5, v18, s[100:101] offset:1024 sc1
	global_load_dword v6, v18, s[100:101] offset:1280 sc1
	global_load_dword v7, v18, s[100:101] offset:1536 sc1
	global_load_dword v8, v18, s[100:101] offset:1792 sc1
	global_load_dword v9, v18, s[100:101] offset:2048 sc1
	global_load_dword v10, v18, s[100:101] offset:2304 sc1
	global_load_dword v11, v18, s[100:101] offset:2560 sc1
	global_load_dword v12, v18, s[100:101] offset:2816 sc1
	global_load_dword v13, v18, s[100:101] offset:3072 sc1
	global_load_dword v14, v18, s[100:101] offset:3328 sc1
	global_load_dword v15, v18, s[100:101] offset:3584 sc1
	global_load_dword v16, v18, s[100:101] offset:3840 sc1
	v_readlane_b32 vcc_hi, v252, 10
	s_lshl_b32 vcc_hi, vcc_hi, 8
	s_add_u32 vcc_hi, vcc_hi, 0x400
	v_mov_b32_e32 v18, vcc_hi
	global_load_dword v18, v18, s[100:101] sc1
	s_waitcnt vmcnt(0)
	v_add_u32_e32 v17, v17, v0
	v_add_u32_e32 v17, v17, v1
	v_add_u32_e32 v17, v17, v4
	v_add_u32_e32 v17, v17, v5
	v_add_u32_e32 v17, v17, v6
	v_add_u32_e32 v17, v17, v7
	v_add_u32_e32 v17, v17, v8
	v_add_u32_e32 v17, v17, v9
	v_add_u32_e32 v17, v17, v10
	v_add_u32_e32 v17, v17, v11
	v_add_u32_e32 v17, v17, v12
	v_add_u32_e32 v17, v17, v13
	v_add_u32_e32 v17, v17, v14
	v_add_u32_e32 v17, v17, v15
	v_add_u32_e32 v17, v17, v16
	v_readfirstlane_b32 vcc_hi, v17
	v_readfirstlane_b32 s99, v18
	s_nop 3
	s_cmp_eq_u32 vcc_hi, vcc_lo
	s_cbranch_scc1 .Lhb7_cenok
	s_sleep 1
	s_sub_u32 m0, m0, 1
	s_cmp_lg_u32 m0, 0
	s_cbranch_scc1 .Lhb7_cen
.Lhb7_cenok:
	s_max_u32 s99, s99, 1
	v_mov_b32_e32 v17, 0x22fc0
	v_mov_b32_e32 v0, s99
	ds_write_b32 v17, v0 offset:4
	s_waitcnt lgkmcnt(0)
.Lhb7_have:
	v_readlane_b32 vcc_hi, v252, 10
	s_lshl_b32 vcc_hi, vcc_hi, 8
	s_add_u32 vcc_hi, vcc_hi, 0x1400
	s_mul_i32 vcc_lo, vcc_lo, s98
	v_mov_b32_e32 v17, vcc_hi
	v_mov_b32_e32 v0, 1
	global_atomic_add v0, v17, v0, s[100:101] sc0
	s_mul_i32 m0, s98, s99
	v_add_u32_e32 v17, 0x1000, v17
	s_waitcnt vmcnt(0)
	v_readfirstlane_b32 vcc_hi, v0
	s_nop 3
	s_add_u32 vcc_hi, vcc_hi, 1
	s_cmp_lg_u32 vcc_hi, m0
	s_cbranch_scc1 .Lhb7_poll
	buffer_wbl2 sc1
	v_mov_b32_e32 v0, s99
	v_mov_b32_e32 v18, 0x3400
	s_waitcnt vmcnt(0)
	global_atomic_add v0, v18, v0, s[100:101] sc0
	s_waitcnt vmcnt(0)
	v_readfirstlane_b32 vcc_hi, v0
	s_nop 3
	s_add_u32 vcc_hi, vcc_hi, s99
	s_cmp_lg_u32 vcc_hi, vcc_lo
	s_cbranch_scc1 .Lhb7_poll
	v_mov_b32_e32 v0, 1
	v_mov_b32_e32 v18, 0x2400
	global_atomic_add v18, v0, s[100:101]
	global_atomic_add v18, v0, s[100:101] offset:256
	global_atomic_add v18, v0, s[100:101] offset:512
	global_atomic_add v18, v0, s[100:101] offset:768
	global_atomic_add v18, v0, s[100:101] offset:1024
	global_atomic_add v18, v0, s[100:101] offset:1280
	global_atomic_add v18, v0, s[100:101] offset:1536
	global_atomic_add v18, v0, s[100:101] offset:1792
	global_atomic_add v18, v0, s[100:101] offset:2048
	global_atomic_add v18, v0, s[100:101] offset:2304
	global_atomic_add v18, v0, s[100:101] offset:2560
	global_atomic_add v18, v0, s[100:101] offset:2816
	global_atomic_add v18, v0, s[100:101] offset:3072
	global_atomic_add v18, v0, s[100:101] offset:3328
	global_atomic_add v18, v0, s[100:101] offset:3584
	global_atomic_add v18, v0, s[100:101] offset:3840

; __device__ __forceinline__ unsigned xb_ld(unsigned* p)              { return __hip_atomic_load(p, __ATOMIC_RELAXED, __HIP_MEMORY_SCOPE_AGENT); }
; __device__ __forceinline__ unsigned xb_add(unsigned* p, unsigned v) { return __hip_atomic_fetch_add(p, v, __ATOMIC_RELAXED, __HIP_MEMORY_SCOPE_AGENT); }
; #define XB_SPIN(cond, bar) do { unsigned _sp = 0; while (cond) { __builtin_amdgcn_s_sleep(1); \
;     if ((++_sp & 255u) == 0u) { if (xb_ld(&(bar)[XB_TMO])) break; if (_sp > XB_SPIN_CAP) { atomicAdd(&(bar)[XB_TMO], 1u); break; } } } } while (0)
; __device__ __forceinline__ void xcd_barrier(const XcdBarrier& b) {
;     ...
;             else XB_SPIN(xb_ld(&bar[XB_TOPGEN]) == tg, bar);
;             __builtin_amdgcn_fence(__ATOMIC_ACQUIRE, "agent");
;             xb_add(&bar[XB_XGEN(b.x)], 1u);
;             asm volatile("s_waitcnt vmcnt(0)" ::: "memory");
;         } else {
;             XB_SPIN(xb_ld(&bar[XB_XGEN(b.x)]) == gen, bar);
;             __builtin_amdgcn_fence(__ATOMIC_ACQUIRE, "agent");
;             asm volatile("s_waitcnt vmcnt(0)" ::: "memory");
;         }
;     }
;     __syncthreads();
.Lhb7_spin:
	global_load_dword v0, v17, s[100:101] sc1
	s_waitcnt vmcnt(0)
	v_readfirstlane_b32 vcc_hi, v0
	s_nop 3
	s_cmp_ge_u32 vcc_hi, s98
	s_cbranch_scc1 .Lhb7_done
	s_sleep 1
	s_sub_u32 s99, s99, 1
	s_cmp_lg_u32 s99, 0
	s_cbranch_scc1 .Lhb7_spin
.Lhb7_done:
	buffer_inv sc1
	s_waitcnt vmcnt(0)
	s_branch .LBB0_1236
	v_mov_b32_e32 v0, s4
	s_waitcnt vmcnt(0) expcnt(0) lgkmcnt(0)
	ds_read_b32 v4, v0
	v_mov_b32_e32 v0, s5
	ds_read_b32 v0, v0
	s_waitcnt lgkmcnt(1)
	v_cmp_ne_u32_e32 vcc, 0, v4
	s_cbranch_vccnz .LBB0_1253
	s_mov_b32 s92, 1
	s_branch .LBB0_1241

; __device__ __forceinline__ void xcd_barrier(const XcdBarrier& b) {
;     ...
;     if (threadIdx.x == 0) {
;         unsigned* bar = b.bar;
;         __builtin_amdgcn_s_waitcnt(0);
;         unsigned nloc = b.st[0], nx = b.st[1];
;         if (nloc == 0u) { xcd_barrier_complete(bar, b.x, nloc, nx); b.st[0] = nloc; b.st[1] = nx; }
.LBB0_1372:
	s_waitcnt vmcnt(0)
	s_waitcnt vmcnt(0)
	s_barrier
	s_mov_b64 s[78:79], exec
	v_readlane_b32 s80, v252, 11
	v_readlane_b32 s81, v252, 12
	s_and_b64 s[80:81], s[78:79], s[80:81]
	s_mov_b64 exec, s[80:81]
	s_cbranch_execz .LBB0_1371
	v_readlane_b32 s98, v252, 4
	v_readlane_b32 s99, v252, 5
	s_load_dword vcc_lo, s[98:99], 0xf8
	v_readlane_b32 s100, v252, 2
	v_readlane_b32 s101, v252, 3
	v_mov_b32_e32 v17, 0x22fc0
	ds_read_b32 v0, v17
	s_waitcnt lgkmcnt(0)
	v_add_u32_e32 v0, 1, v0
	ds_write_b32 v17, v0
	s_nop 0
	v_readfirstlane_b32 s98, v0
	ds_read_b32 v0, v17 offset:4
	s_waitcnt lgkmcnt(0)
	v_readfirstlane_b32 s99, v0
	s_mov_b32 m0, 0x400
	s_cmp_lg_u32 s99, 0
	s_cbranch_scc1 .Lhb8_have

; __device__ __forceinline__ unsigned xb_ld(unsigned* p)              { return __hip_atomic_load(p, __ATOMIC_RELAXED, __HIP_MEMORY_SCOPE_AGENT); }
; __device__ __forceinline__ unsigned xb_add(unsigned* p, unsigned v) { return __hip_atomic_fetch_add(p, v, __ATOMIC_RELAXED, __HIP_MEMORY_SCOPE_AGENT); }
; #define XB_SPIN(cond, bar) do { unsigned _sp = 0; while (cond) { __builtin_amdgcn_s_sleep(1); \
;     if ((++_sp & 255u) == 0u) { if (xb_ld(&(bar)[XB_TMO])) break; if (_sp > XB_SPIN_CAP) { atomicAdd(&(bar)[XB_TMO], 1u); break; } } } } while (0)
; __device__ __forceinline__ void xcd_barrier(const XcdBarrier& b) {
;     ...
;             __builtin_amdgcn_fence(__ATOMIC_ACQUIRE, "agent");
;             xb_add(&bar[XB_XGEN(b.x)], 1u);
;             asm volatile("s_waitcnt vmcnt(0)" ::: "memory");
;         } else {
;             XB_SPIN(xb_ld(&bar[XB_XGEN(b.x)]) == gen, bar);
;             __builtin_amdgcn_fence(__ATOMIC_ACQUIRE, "agent");
;             asm volatile("s_waitcnt vmcnt(0)" ::: "memory");
;         }
;     }
;     __syncthreads();
.Lhb8_done:
	buffer_inv sc1
	s_waitcnt vmcnt(0)
	s_branch .LBB0_1371
	v_mov_b32_e32 v0, s95
	s_waitcnt vmcnt(0) expcnt(0) lgkmcnt(0)
	ds_read_b32 v4, v0
	v_mov_b32_e32 v0, s96
	ds_read_b32 v0, v0
	s_waitcnt lgkmcnt(1)
	v_cmp_ne_u32_e32 vcc, 0, v4
	s_cbranch_vccnz .LBB0_1388
	s_mov_b32 s86, 1
	s_branch .LBB0_1376
